# P0 rows loop: exposed tail of the 16-head transpose-reduce via v_permlane16_swap and DPP (row_ror:8, row_shl/shr:4, quad_perm) instead of five dependent ds_bpermute round trips
# speedup vs baseline: 1.0019x; 1.0009x over previous
.Lp0rows_nopf:
	s_waitcnt lgkmcnt(1)
	v_fmac_f32_e32 v23, v230, v0
	v_fma_f32 v29, v232, v72, 0
	v_fma_f32 v62, v224, v188, 0
	v_fma_f32 v55, v232, v192, 0
	v_fmac_f32_e32 v52, v226, v18
	v_fmac_f32_e32 v40, v227, v11
	v_fmac_f32_e32 v32, v235, v15
	v_fmac_f32_e32 v54, v226, v154
	v_fmac_f32_e32 v61, v234, v158
	v_fmac_f32_e32 v53, v227, v139
	v_fmac_f32_e32 v35, v235, v143
	v_add_f32_e32 v16, v34, v43
	v_fmac_f32_e32 v23, v231, v1
	v_fmac_f32_e32 v29, v233, v73
	v_fma_f32 v25, v224, v80, 0
	v_fma_f32 v30, v232, v84, 0
	v_fmac_f32_e32 v62, v225, v189
	v_fmac_f32_e32 v55, v233, v193
	v_fma_f32 v63, v224, v200, 0
	v_fma_f32 v65, v232, v246, 0
	v_fmac_f32_e32 v52, v227, v19
	v_add_f32_e32 v9, v40, v32
	v_fmac_f32_e32 v54, v227, v155
	v_fmac_f32_e32 v61, v235, v159
	v_add_f32_e32 v17, v53, v35
	v_fmac_f32_e32 v23, v226, v2
	v_cndmask_b32_e64 v1, v8, v16, s[8:9]
	v_fma_f32 v31, v224, v92, 0
	v_fma_f32 v26, v232, v100, 0
	v_fmac_f32_e32 v29, v228, v74
	v_fmac_f32_e32 v25, v225, v81
	v_fmac_f32_e32 v30, v233, v85
	v_fmac_f32_e32 v62, v222, v190
	v_fmac_f32_e32 v55, v228, v194
	v_fmac_f32_e32 v63, v225, v201
	v_fmac_f32_e32 v65, v233, v247
	v_add_f32_e32 v10, v52, v60
	v_add_f32_e32 v18, v54, v61
	v_fmac_f32_e32 v23, v227, v3
	ds_bpermute_b32 v1, v241, v1
	v_cndmask_b32_e64 v3, v9, v17, s[8:9]
	v_fmac_f32_e32 v31, v225, v93
	v_fmac_f32_e32 v26, v233, v101
	v_fmac_f32_e32 v64, v223, v67
	v_fmac_f32_e32 v29, v229, v75
	v_fmac_f32_e32 v25, v222, v82
	v_fmac_f32_e32 v30, v228, v86
	v_fmac_f32_e32 v62, v223, v191
	v_fmac_f32_e32 v55, v229, v195
	v_fmac_f32_e32 v63, v222, v202
	v_fmac_f32_e32 v65, v228, v248
	s_waitcnt lgkmcnt(1)
	v_fmac_f32_e32 v24, v236, v4
	ds_bpermute_b32 v3, v241, v3
	v_cndmask_b32_e64 v4, v10, v18, s[8:9]
	v_fmac_f32_e32 v31, v222, v94
	v_fmac_f32_e32 v26, v228, v102
	v_fmac_f32_e32 v64, v230, v36
	v_fmac_f32_e32 v29, v236, v44
	v_fmac_f32_e32 v25, v223, v83
	v_fmac_f32_e32 v30, v229, v87
	v_fmac_f32_e32 v62, v230, v172
	v_fmac_f32_e32 v55, v236, v180
	v_fmac_f32_e32 v63, v223, v203
	v_fmac_f32_e32 v65, v229, v249
	ds_bpermute_b32 v4, v241, v4
	v_fmac_f32_e32 v31, v223, v95
	v_fmac_f32_e32 v26, v229, v103
	v_fmac_f32_e32 v64, v231, v37
	v_fmac_f32_e32 v29, v237, v45
	v_fmac_f32_e32 v25, v230, v48
	v_fmac_f32_e32 v30, v236, v56
	v_fmac_f32_e32 v62, v231, v173
	v_fmac_f32_e32 v55, v237, v181
	v_fmac_f32_e32 v63, v230, v196
	v_fmac_f32_e32 v65, v236, v204
	v_fmac_f32_e32 v31, v230, v68
	v_fmac_f32_e32 v26, v236, v76
	v_fmac_f32_e32 v64, v226, v38
	v_fmac_f32_e32 v29, v234, v46
	v_fmac_f32_e32 v25, v231, v49
	v_fmac_f32_e32 v30, v237, v57
	v_fmac_f32_e32 v62, v226, v174
	v_fmac_f32_e32 v55, v234, v182
	v_fmac_f32_e32 v63, v231, v197
	v_fmac_f32_e32 v65, v237, v205
	v_cndmask_b32_e64 v2, v16, v8, s[8:9]
	v_fmac_f32_e32 v31, v231, v69
	v_fmac_f32_e32 v26, v237, v77
	v_fmac_f32_e32 v64, v227, v39
	v_fmac_f32_e32 v29, v235, v47
	v_fmac_f32_e32 v25, v226, v50
	v_fmac_f32_e32 v30, v234, v58
	v_fmac_f32_e32 v62, v227, v175
	v_fmac_f32_e32 v55, v235, v183
	v_fmac_f32_e32 v63, v226, v198
	v_fmac_f32_e32 v65, v234, v206
	s_waitcnt lgkmcnt(2)
	v_add_f32_e32 v1, v2, v1
	v_cndmask_b32_e64 v2, v17, v9, s[8:9]
	v_fma_f32 v27, v224, v104, 0
	v_fma_f32 v33, v232, v112, 0
	v_fma_f32 v41, v224, v128, 0
	v_fma_f32 v42, v232, v132, 0
	v_fmac_f32_e32 v31, v226, v70
	v_fmac_f32_e32 v26, v234, v78
	v_add_f32_e32 v11, v64, v29
	v_fmac_f32_e32 v25, v227, v51
	v_fmac_f32_e32 v30, v235, v59
	v_add_f32_e32 v19, v62, v55
	v_fmac_f32_e32 v63, v227, v199
	v_fmac_f32_e32 v65, v235, v207
	s_waitcnt lgkmcnt(1)
	v_add_f32_e32 v2, v2, v3
	v_cndmask_b32_e64 v3, v18, v10, s[8:9]
	v_fmac_f32_e32 v27, v225, v105
	v_fmac_f32_e32 v33, v233, v113
	v_fmac_f32_e32 v41, v225, v129
	v_fmac_f32_e32 v42, v233, v133
	v_fmac_f32_e32 v31, v227, v71
	v_fmac_f32_e32 v26, v235, v79
	v_add_f32_e32 v12, v25, v30
	v_add_f32_e32 v20, v63, v65
	v_fmac_f32_e32 v24, v237, v5
	s_waitcnt lgkmcnt(0)
	v_add_f32_e32 v3, v3, v4
	v_cndmask_b32_e64 v4, v11, v19, s[8:9]
	v_fmac_f32_e32 v27, v222, v106
	v_fmac_f32_e32 v33, v228, v114
	v_fmac_f32_e32 v41, v222, v130
	v_fmac_f32_e32 v42, v228, v134
	v_add_f32_e32 v13, v31, v26
	v_add_f32_e32 v21, v66, v21
	v_fmac_f32_e32 v24, v234, v6
	ds_bpermute_b32 v4, v241, v4
	v_cndmask_b32_e64 v6, v12, v20, s[8:9]
	v_fmac_f32_e32 v27, v223, v107
	v_fmac_f32_e32 v33, v229, v115
	v_fmac_f32_e32 v41, v223, v131
	v_fmac_f32_e32 v42, v229, v135
	v_fmac_f32_e32 v24, v235, v7
	ds_bpermute_b32 v6, v241, v6
	v_cndmask_b32_e64 v7, v13, v21, s[8:9]
	v_fmac_f32_e32 v27, v230, v88
	v_fmac_f32_e32 v33, v236, v96
	v_fmac_f32_e32 v41, v230, v108
	v_fmac_f32_e32 v42, v236, v116
	ds_bpermute_b32 v7, v241, v7
	v_fmac_f32_e32 v27, v231, v89
	v_fmac_f32_e32 v33, v237, v97
	v_fmac_f32_e32 v41, v231, v109
	v_fmac_f32_e32 v42, v237, v117
	v_fmac_f32_e32 v27, v226, v90
	v_fmac_f32_e32 v33, v234, v98
	v_fmac_f32_e32 v41, v226, v110
	v_fmac_f32_e32 v42, v234, v118
	v_cndmask_b32_e64 v5, v19, v11, s[8:9]
	v_fmac_f32_e32 v27, v227, v91
	v_fmac_f32_e32 v33, v235, v99
	v_fmac_f32_e32 v41, v227, v111
	v_fmac_f32_e32 v42, v235, v119
	s_waitcnt lgkmcnt(2)
	v_add_f32_e32 v4, v5, v4
	v_cndmask_b32_e64 v5, v20, v12, s[8:9]
	v_add_f32_e32 v14, v27, v33
	v_add_f32_e32 v15, v41, v42
	v_add_f32_e32 v0, v23, v24
	s_waitcnt lgkmcnt(1)
	v_add_f32_e32 v5, v5, v6
	v_cndmask_b32_e64 v6, v21, v13, s[8:9]
	s_waitcnt lgkmcnt(0)
	v_add_f32_e32 v6, v6, v7
	v_cndmask_b32_e64 v7, v14, v22, s[8:9]
	v_cndmask_b32_e64 v9, v15, v0, s[8:9]
	ds_bpermute_b32 v7, v241, v7
	ds_bpermute_b32 v9, v241, v9
	v_cndmask_b32_e64 v8, v22, v14, s[8:9]
	v_cndmask_b32_e64 v0, v0, v15, s[8:9]
	s_waitcnt lgkmcnt(1)
	v_add_f32_e32 v7, v8, v7
	s_waitcnt lgkmcnt(0)
	v_add_f32_e32 v0, v0, v9
	s_nop 1
	v_permlane16_swap_b32_e32 v1, v5
	v_permlane16_swap_b32_e32 v2, v6
	v_permlane16_swap_b32_e32 v3, v7
	v_permlane16_swap_b32_e32 v4, v0
	v_add_f32_e32 v1, v1, v5
	v_add_f32_e32 v2, v2, v6
	v_add_f32_e32 v3, v3, v7
	v_add_f32_e32 v0, v4, v0
	v_cndmask_b32_e64 v4, v1, v3, s[12:13]
	v_cndmask_b32_e64 v5, v2, v0, s[12:13]
	v_cndmask_b32_e64 v1, v3, v1, s[12:13]
	v_cndmask_b32_e64 v0, v0, v2, s[12:13]
	s_nop 1
	v_add_f32_dpp v1, v4, v1 row_ror:8 row_mask:0xf bank_mask:0xf
	v_add_f32_dpp v0, v5, v0 row_ror:8 row_mask:0xf bank_mask:0xf
	v_cndmask_b32_e64 v2, v1, v0, s[14:15]
	v_cndmask_b32_e64 v0, v0, v1, s[14:15]
	s_nop 1
	v_mov_b32_dpp v3, v2 row_shl:4 row_mask:0xf bank_mask:0x5
	v_mov_b32_dpp v3, v2 row_shr:4 row_mask:0xf bank_mask:0xa
	s_nop 1
	v_add_f32_e32 v0, v0, v3
	s_nop 1
	v_add_f32_dpp v0, v0, v0 quad_perm:[2,3,0,1] row_mask:0xf bank_mask:0xf
	s_nop 1
	v_add_f32_dpp v0, v0, v0 quad_perm:[1,0,3,2] row_mask:0xf bank_mask:0xf
	s_and_saveexec_b64 s[18:19], s[16:17]
	s_cbranch_execz .LBB0_109
	s_ashr_i32 s44, s36, 8
	s_and_b32 s51, s36, 0xfff
	v_add_f32_e32 v2, v0, v245
	v_mul_f32_e64 v0, |v2|, s50
	v_exp_f32_e32 v3, v0
	v_and_or_b32 v0, s44, -16, v243
	v_ashrrev_i32_e32 v1, 31, v0
	v_lshlrev_b64 v[0:1], 14, v[0:1]
	v_add_f32_e32 v3, 1.0, v3
	v_log_f32_e32 v3, v3
	s_lshl_b32 s44, s51, 2
	v_lshl_add_u64 v[0:1], s[42:43], 0, v[0:1]
	v_min_f32_e32 v2, 0, v2
	v_fmac_f32_e32 v2, 0xbf317218, v3
	v_lshl_add_u64 v[0:1], v[0:1], 0, s[44:45]
	global_store_dword v[0:1], v2, off
	s_branch .LBB0_109
